# Y-slab L2 prefetch staged finer: 4 tiles every 4 iterations, 3-6 tiles ahead, by the first two MFMA-only waves
# speedup vs baseline: 1.0014x; 1.0012x over previous
; DI f32x4 mfma16(bf16x8 a, bf16x8 b, f32x4 c) { return __builtin_amdgcn_mfma_f32_16x16x32_bf16(a, b, c, 0, 0, 0); }
; template <int N> DI void wait_vm() { asm volatile("s_waitcnt vmcnt(%0)" ::"n"(N) : "memory"); }
; DI void raw_barrier() { asm volatile("" ::: "memory"); __builtin_amdgcn_s_barrier(); asm volatile("" ::: "memory"); }
;     ...
;     auto compute = [&](int cb, bool do_issue, int ikt, int ib) {
;         const char* base = lds + cb * BUF;
;         bf16x8 af[MT], bfr[NT];
; #pragma unroll
;         for (int nt = 0; nt < NT; ++nt) {
;             const int br = BM + (nt / NTS) * (BN / NSEG) + wc * (NTS * 16) + (nt % NTS) * 16;
;             bfr[nt] = *(const bf16x8*)(base + (br + l15) * 64 + rsw);
;         }
; #pragma unroll
;         for (int mt = 0; mt < MT; ++mt) af[mt] = *(const bf16x8*)(base + (wr * WM + mt * 16 + l15) * 64 + rsw);
;         constexpr int TOT = MT * NT, PER = (TOT + NIT - 1) / NIT;
; #pragma unroll
;         for (int part = 0; part < NIT; ++part) {
; #pragma unroll
;             for (int q = 0; q < PER; ++q) {
;                 const int idx = part * PER + q;
;                 if (idx < TOT) {
;                     const int mt = idx / NT, nt = idx % NT;
;                     acc[mt][nt] = SWAP ? mfma16(bfr[nt], af[mt], acc[mt][nt]) : mfma16(af[mt], bfr[nt], acc[mt][nt]);
;                 }
;             }
;             __builtin_amdgcn_sched_barrier(0);
;             if (do_issue) issue_one(ikt, ib, part);
;             __builtin_amdgcn_sched_barrier(0);
;         }
;     };
;     __syncthreads();
; #pragma unroll
;     for (int d = 0; d < D; ++d) issue(d, d);
;     int cb = 0, ib = D;
;     for (int kt = 0; kt < KT; ++kt) {
;         if (D > 1 && kt + D - 1 < KT) wait_vm<(D - 1) * NIT>(); else wait_vm<0>();
;         raw_barrier();
.Lpo1_c_entry:
	v_subrev_u32_e32 v246, 0x100, v212
	v_readfirstlane_b32 s96, v130
	v_readfirstlane_b32 s97, v131
	v_readfirstlane_b32 s94, v0
	s_nop 3
	s_sub_u32 s96, s96, s94
	s_subb_u32 s97, s97, 0
	s_add_i32 s94, s33, 2
	v_lshrrev_b32_e32 v247, 5, v246
	v_add_u32_e32 v247, s94, v247
	v_and_b32_e32 v247, 31, v247
	v_and_b32_e32 v199, 31, v246
	v_lshlrev_b32_e32 v199, 7, v199
	v_lshl_or_b32 v247, v247, 12, v199
	s_nop 1
	global_load_dword v247, v247, s[96:97]
	v_readfirstlane_b32 s95, v246
	s_nop 3
	s_lshr_b32 s95, s95, 6
	s_mov_b32 s9, 2
	s_waitcnt vmcnt(1)
	s_barrier
	v_add_u32_e32 v197, v140, v141
	v_add_u32_e32 v196, v140, v139
	ds_read_b128 v[146:149], v196
	ds_read_b128 v[154:157], v196 offset:1024
	ds_read_b128 v[182:185], v196 offset:2048
	ds_read_b128 v[142:145], v197 offset:4096
	ds_read_b128 v[150:153], v197 offset:5120
	ds_read_b128 v[158:161], v197 offset:6144
	ds_read_b128 v[162:165], v197 offset:7168
	ds_read_b128 v[166:169], v197 offset:8192
	ds_read_b128 v[170:173], v197 offset:9216
	ds_read_b128 v[174:177], v197 offset:10240
	ds_read_b128 v[178:181], v197 offset:11264
	ds_read_b128 v[186:189], v196 offset:3072
.Lpo1_c_loop:
	s_bitcmp1_b32 s9, 0
	s_cselect_b32 s46, 0, 0x11000
	v_add_u32_e32 v198, s46, v140
	v_add_u32_e32 v197, v198, v141
	v_add_u32_e32 v196, v198, v139
	s_waitcnt lgkmcnt(8)
	v_mfma_f32_16x16x32_bf16 v[98:101], v[142:145], v[146:149], v[98:101]
	s_waitcnt lgkmcnt(7)
	v_mfma_f32_16x16x32_bf16 v[94:97], v[150:153], v[146:149], v[94:97]
	s_waitcnt lgkmcnt(6)
	v_mfma_f32_16x16x32_bf16 v[90:93], v[158:161], v[146:149], v[90:93]
	s_waitcnt lgkmcnt(5)
	v_mfma_f32_16x16x32_bf16 v[86:89], v[162:165], v[146:149], v[86:89]
	s_waitcnt lgkmcnt(4)
	v_mfma_f32_16x16x32_bf16 v[82:85], v[166:169], v[146:149], v[82:85]
	s_waitcnt lgkmcnt(3)
	v_mfma_f32_16x16x32_bf16 v[78:81], v[170:173], v[146:149], v[78:81]
	s_waitcnt lgkmcnt(2)
	v_mfma_f32_16x16x32_bf16 v[74:77], v[174:177], v[146:149], v[74:77]
	s_waitcnt lgkmcnt(1)
	v_mfma_f32_16x16x32_bf16 v[70:73], v[178:181], v[146:149], v[70:73]
	s_waitcnt lgkmcnt(0)
	s_barrier
	ds_read_b128 v[146:149], v196
	s_and_b32 s94, s9, 3
	s_cmp_lg_u32 s94, 2
	s_cbranch_scc1 .Lpo1_ypf_skip
	s_cmp_gt_u32 s95, 1
	s_cbranch_scc1 .Lpo1_ypf_skip
	s_add_i32 s94, s33, s9
	s_add_i32 s94, s94, 3
	v_lshrrev_b32_e32 v199, 5, v246
	v_add_u32_e32 v199, s94, v199
	v_and_b32_e32 v199, 31, v199
	v_lshlrev_b32_e32 v199, 5, v199
	v_and_or_b32 v199, v246, 31, v199
	v_lshlrev_b32_e32 v199, 7, v199
	global_load_dword v247, v199, s[96:97]

; DI f32x4 mfma16(bf16x8 a, bf16x8 b, f32x4 c) { return __builtin_amdgcn_mfma_f32_16x16x32_bf16(a, b, c, 0, 0, 0); }
; template <int N> DI void wait_vm() { asm volatile("s_waitcnt vmcnt(%0)" ::"n"(N) : "memory"); }
; DI void raw_barrier() { asm volatile("" ::: "memory"); __builtin_amdgcn_s_barrier(); asm volatile("" ::: "memory"); }
;     ...
;     auto compute = [&](int cb, bool do_issue, int ikt, int ib) {
;         const char* base = lds + cb * BUF;
;         bf16x8 af[MT], bfr[NT];
; #pragma unroll
;         for (int nt = 0; nt < NT; ++nt) {
;             const int br = BM + (nt / NTS) * (BN / NSEG) + wc * (NTS * 16) + (nt % NTS) * 16;
;             bfr[nt] = *(const bf16x8*)(base + (br + l15) * 64 + rsw);
;         }
; #pragma unroll
;         for (int mt = 0; mt < MT; ++mt) af[mt] = *(const bf16x8*)(base + (wr * WM + mt * 16 + l15) * 64 + rsw);
;         constexpr int TOT = MT * NT, PER = (TOT + NIT - 1) / NIT;
; #pragma unroll
;         for (int part = 0; part < NIT; ++part) {
; #pragma unroll
;             for (int q = 0; q < PER; ++q) {
;                 const int idx = part * PER + q;
;                 if (idx < TOT) {
;                     const int mt = idx / NT, nt = idx % NT;
;                     acc[mt][nt] = SWAP ? mfma16(bfr[nt], af[mt], acc[mt][nt]) : mfma16(af[mt], bfr[nt], acc[mt][nt]);
;                 }
;             }
;             __builtin_amdgcn_sched_barrier(0);
;             if (do_issue) issue_one(ikt, ib, part);
;             __builtin_amdgcn_sched_barrier(0);
;         }
;     };
;     __syncthreads();
; #pragma unroll
;     for (int d = 0; d < D; ++d) issue(d, d);
;     int cb = 0, ib = D;
;     for (int kt = 0; kt < KT; ++kt) {
;         if (D > 1 && kt + D - 1 < KT) wait_vm<(D - 1) * NIT>(); else wait_vm<0>();
;         raw_barrier();
.Lpo2_c_entry:
	v_subrev_u32_e32 v246, 0x100, v212
	v_readfirstlane_b32 s96, v130
	v_readfirstlane_b32 s97, v131
	v_readfirstlane_b32 s94, v0
	s_nop 3
	s_sub_u32 s96, s96, s94
	s_subb_u32 s97, s97, 0
	s_add_i32 s94, s33, 2
	v_lshrrev_b32_e32 v247, 5, v246
	v_add_u32_e32 v247, s94, v247
	v_and_b32_e32 v247, 31, v247
	v_and_b32_e32 v199, 31, v246
	v_lshlrev_b32_e32 v199, 7, v199
	v_lshl_or_b32 v247, v247, 12, v199
	s_nop 1
	global_load_dword v247, v247, s[96:97]
	v_readfirstlane_b32 s95, v246
	s_nop 3
	s_lshr_b32 s95, s95, 6
	s_mov_b32 s29, 2
	s_waitcnt vmcnt(1)
	s_barrier
	v_add_u32_e32 v197, v140, v141
	v_add_u32_e32 v196, v140, v139
	ds_read_b128 v[146:149], v196
	ds_read_b128 v[154:157], v196 offset:1024
	ds_read_b128 v[182:185], v196 offset:2048
	ds_read_b128 v[142:145], v197 offset:4096
	ds_read_b128 v[150:153], v197 offset:5120
	ds_read_b128 v[158:161], v197 offset:6144
	ds_read_b128 v[162:165], v197 offset:7168
	ds_read_b128 v[166:169], v197 offset:8192
	ds_read_b128 v[170:173], v197 offset:9216
	ds_read_b128 v[174:177], v197 offset:10240
	ds_read_b128 v[178:181], v197 offset:11264
	ds_read_b128 v[186:189], v196 offset:3072
.Lpo2_c_loop:
	s_bitcmp1_b32 s29, 0
	s_cselect_b32 s46, 0, 0x11000
	v_add_u32_e32 v198, s46, v140
	v_add_u32_e32 v197, v198, v141
	v_add_u32_e32 v196, v198, v139
	s_waitcnt lgkmcnt(8)
	v_mfma_f32_16x16x32_bf16 v[98:101], v[142:145], v[146:149], v[98:101]
	s_waitcnt lgkmcnt(7)
	v_mfma_f32_16x16x32_bf16 v[94:97], v[150:153], v[146:149], v[94:97]
	s_waitcnt lgkmcnt(6)
	v_mfma_f32_16x16x32_bf16 v[90:93], v[158:161], v[146:149], v[90:93]
	s_waitcnt lgkmcnt(5)
	v_mfma_f32_16x16x32_bf16 v[86:89], v[162:165], v[146:149], v[86:89]
	s_waitcnt lgkmcnt(4)
	v_mfma_f32_16x16x32_bf16 v[82:85], v[166:169], v[146:149], v[82:85]
	s_waitcnt lgkmcnt(3)
	v_mfma_f32_16x16x32_bf16 v[78:81], v[170:173], v[146:149], v[78:81]
	s_waitcnt lgkmcnt(2)
	v_mfma_f32_16x16x32_bf16 v[74:77], v[174:177], v[146:149], v[74:77]
	s_waitcnt lgkmcnt(1)
	v_mfma_f32_16x16x32_bf16 v[70:73], v[178:181], v[146:149], v[70:73]
	s_waitcnt lgkmcnt(0)
	s_barrier
	ds_read_b128 v[146:149], v196
	s_and_b32 s94, s29, 3
	s_cmp_lg_u32 s94, 2
	s_cbranch_scc1 .Lpo2_ypf_skip
	s_cmp_gt_u32 s95, 1
	s_cbranch_scc1 .Lpo2_ypf_skip
	s_add_i32 s94, s33, s29
	s_add_i32 s94, s94, 3
	v_lshrrev_b32_e32 v199, 5, v246
	v_add_u32_e32 v199, s94, v199
	v_and_b32_e32 v199, 31, v199
	v_lshlrev_b32_e32 v199, 5, v199
	v_and_or_b32 v199, v246, 31, v199
	v_lshlrev_b32_e32 v199, 7, v199
	global_load_dword v247, v199, s[96:97]
